# QKV rotary epilogue: cos/sin table fetches software-pipelined one row group ahead (second register set), counted waits
# speedup vs baseline: 1.0300x; 1.0007x over previous
; __device__ __forceinline__ v4u pk8(f32x4 a, f32x4 b) { v4u w; w.x = pk2(a[0], a[1]); w.y = pk2(a[2], a[3]); w.z = pk2(b[0], b[1]); w.w = pk2(b[2], b[3]); return w; }
;     __device__ __forceinline__ void operator()(const accv (&acc)[2][2][4][2], const pg8::Unit& u, int wr, int wc, int fr, int fq) const {
;     ...
;                 for (int m = 0; m < 4; ++m) { const int row = row0 + ai * 128 + m * 16, pos = row & 4095;
;                     f32x4 o1[2], o2[2];
; #pragma unroll
;                     for (int n = 0; n < 2; ++n) { const f32x4 cv = *(const f32x4*)(rc + (unsigned)(pos * 64 + d0 + 4 * n)), sv = *(const f32x4*)(rs + (unsigned)(pos * 64 + d0 + 4 * n));
;                         const f32x4 x1 = acc[ai][0][m][n], x2 = acc[ai][1][m][n];
;                         o1[n] = (x1 * cv - x2 * sv) * sc; o2[n] = (x2 * cv + x1 * sv) * sc; }
;                     bf16* p = dst + (unsigned)(row * 1024 + head * 128 + d0);
;                     *(v4u*)p = pk8(o1[0], o1[1]); *(v4u*)(p + 64) = pk8(o2[0], o2[1]);
;                     asm volatile("" ::: "memory"); }
.LBB0_547:
	v_lshlrev_b32_e32 v148, 6, v147
	v_and_or_b32 v148, v148, s96, v144
	v_lshlrev_b32_e32 v160, 2, v148
	global_load_dwordx4 v[148:151], v160, s[72:73] offset:16
	global_load_dwordx4 v[152:155], v160, s[72:73]
	global_load_dwordx4 v[156:159], v160, s[74:75] offset:16
	s_nop 0
	global_load_dwordx4 v[160:163], v160, s[74:75]
	s_cmp_lt_u32 s14, 4
	s_cselect_b64 vcc, -1, 0
	s_and_b64 s[2:3], vcc, exec
	v_mov_b32_e32 v140, 0x3e0293ee
	s_cselect_b32 s87, s1, s18
	s_cselect_b32 s86, s0, s25
	s_lshl_b32 s2, s79, 8
	v_cndmask_b32_e32 v140, 1.0, v140, vcc
	s_or_b32 s81, s2, s28
	v_or3_b32 v168, v146, s81, v144
	v_lshl_add_u64 v[170:171], v[168:169], 1, s[86:87]
	s_mov_b32 s2, 0x3f7c0
	s_mov_b32 s3, 0x3fbc0
	s_mov_b32 s12, 0x3ffc0
	v_mov_b32_e32 v209, 0
	v_or_b32_e32 v208, 16, v147
	v_lshlrev_b32_e32 v192, 6, v208
	v_and_or_b32 v192, v192, s2, v144
	v_lshlrev_b32_e32 v204, 2, v192
	global_load_dwordx4 v[192:195], v204, s[72:73] offset:16
	global_load_dwordx4 v[196:199], v204, s[72:73]
	global_load_dwordx4 v[200:203], v204, s[74:75] offset:16
	s_nop 0
	global_load_dwordx4 v[204:207], v204, s[74:75]
	s_waitcnt vmcnt(4)
	v_pk_mul_f32 v[164:165], v[110:111], v[162:163]
	v_pk_mul_f32 v[166:167], v[108:109], v[160:161]
	v_pk_mul_f32 v[162:163], v[126:127], v[162:163]
	v_pk_mul_f32 v[160:161], v[124:125], v[160:161]
	v_pk_fma_f32 v[164:165], v[126:127], v[154:155], v[164:165] neg_lo:[0,0,1] neg_hi:[0,0,1]
	v_pk_fma_f32 v[166:167], v[124:125], v[152:153], v[166:167] neg_lo:[0,0,1] neg_hi:[0,0,1]
	v_pk_fma_f32 v[154:155], v[110:111], v[154:155], v[162:163]
	v_pk_fma_f32 v[152:153], v[108:109], v[152:153], v[160:161]
	v_pk_mul_f32 v[160:161], v[106:107], v[158:159]
	v_pk_mul_f32 v[162:163], v[104:105], v[156:157]
	v_pk_fma_f32 v[160:161], v[122:123], v[150:151], v[160:161] neg_lo:[0,0,1] neg_hi:[0,0,1]
	v_pk_fma_f32 v[162:163], v[120:121], v[148:149], v[162:163] neg_lo:[0,0,1] neg_hi:[0,0,1]
	v_pk_mul_f32 v[158:159], v[122:123], v[158:159]
	v_pk_mul_f32 v[156:157], v[120:121], v[156:157]
	v_pk_mul_f32 v[164:165], v[140:141], v[164:165] op_sel_hi:[0,1]
	v_pk_mul_f32 v[166:167], v[140:141], v[166:167] op_sel_hi:[0,1]
	v_pk_mul_f32 v[160:161], v[140:141], v[160:161] op_sel_hi:[0,1]
	v_pk_mul_f32 v[162:163], v[140:141], v[162:163] op_sel_hi:[0,1]
	v_pk_fma_f32 v[150:151], v[106:107], v[150:151], v[158:159]
	v_pk_fma_f32 v[148:149], v[104:105], v[148:149], v[156:157]
	v_pk_mul_f32 v[154:155], v[140:141], v[154:155] op_sel_hi:[0,1]
	v_pk_mul_f32 v[152:153], v[140:141], v[152:153] op_sel_hi:[0,1]
	v_pk_mul_f32 v[156:157], v[140:141], v[150:151] op_sel_hi:[0,1]
	v_pk_mul_f32 v[158:159], v[140:141], v[148:149] op_sel_hi:[0,1]
	v_cvt_pk_bf16_f32 v148, v166, v167
	v_cvt_pk_bf16_f32 v149, v164, v165
	v_cvt_pk_bf16_f32 v150, v162, v163
	v_cvt_pk_bf16_f32 v151, v160, v161
	global_store_dwordx4 v[170:171], v[148:151], off
	s_nop 1
	v_cvt_pk_bf16_f32 v148, v152, v153
	v_cvt_pk_bf16_f32 v149, v154, v155
	v_cvt_pk_bf16_f32 v150, v158, v159
	v_cvt_pk_bf16_f32 v151, v156, v157
	global_store_dwordx4 v[170:171], v[148:151], off offset:128
	s_nop 1
	v_or_b32_e32 v168, 32, v147
	v_lshlrev_b32_e32 v148, 6, v168
	v_and_or_b32 v148, v148, s3, v144
	v_lshlrev_b32_e32 v160, 2, v148
	global_load_dwordx4 v[148:151], v160, s[72:73] offset:16
	global_load_dwordx4 v[152:155], v160, s[72:73]
	global_load_dwordx4 v[156:159], v160, s[74:75] offset:16
	s_nop 0
	global_load_dwordx4 v[160:163], v160, s[74:75]
	s_waitcnt vmcnt(6)
	v_pk_mul_f32 v[164:165], v[94:95], v[206:207]
	v_pk_mul_f32 v[206:207], v[118:119], v[206:207]
	v_pk_mul_f32 v[166:167], v[92:93], v[204:205]
	v_pk_fma_f32 v[164:165], v[118:119], v[198:199], v[164:165] neg_lo:[0,0,1] neg_hi:[0,0,1]
	v_pk_mul_f32 v[204:205], v[116:117], v[204:205]
	v_pk_fma_f32 v[198:199], v[94:95], v[198:199], v[206:207]
	v_pk_mul_f32 v[206:207], v[88:89], v[200:201]
	v_pk_mul_f32 v[200:201], v[112:113], v[200:201]
	v_pk_fma_f32 v[166:167], v[116:117], v[196:197], v[166:167] neg_lo:[0,0,1] neg_hi:[0,0,1]
	v_pk_fma_f32 v[196:197], v[92:93], v[196:197], v[204:205]
	v_pk_mul_f32 v[204:205], v[90:91], v[202:203]
	v_pk_fma_f32 v[206:207], v[112:113], v[192:193], v[206:207] neg_lo:[0,0,1] neg_hi:[0,0,1]
	v_pk_mul_f32 v[202:203], v[114:115], v[202:203]
	v_pk_fma_f32 v[192:193], v[88:89], v[192:193], v[200:201]
	v_pk_fma_f32 v[204:205], v[114:115], v[194:195], v[204:205] neg_lo:[0,0,1] neg_hi:[0,0,1]
	v_pk_fma_f32 v[194:195], v[90:91], v[194:195], v[202:203]
	v_pk_mul_f32 v[202:203], v[140:141], v[192:193] op_sel_hi:[0,1]
	v_lshlrev_b32_e32 v192, 10, v208
	v_pk_mul_f32 v[164:165], v[140:141], v[164:165] op_sel_hi:[0,1]
	v_pk_mul_f32 v[166:167], v[140:141], v[166:167] op_sel_hi:[0,1]
	v_pk_mul_f32 v[204:205], v[140:141], v[204:205] op_sel_hi:[0,1]
	v_pk_mul_f32 v[206:207], v[140:141], v[206:207] op_sel_hi:[0,1]
	v_or3_b32 v208, v192, s81, v144
	v_pk_mul_f32 v[198:199], v[140:141], v[198:199] op_sel_hi:[0,1]
	v_pk_mul_f32 v[196:197], v[140:141], v[196:197] op_sel_hi:[0,1]
	v_pk_mul_f32 v[200:201], v[140:141], v[194:195] op_sel_hi:[0,1]
	v_lshl_add_u64 v[210:211], v[208:209], 1, s[86:87]
	v_cvt_pk_bf16_f32 v192, v166, v167
	v_cvt_pk_bf16_f32 v193, v164, v165
	v_cvt_pk_bf16_f32 v194, v206, v207
	v_cvt_pk_bf16_f32 v195, v204, v205
	global_store_dwordx4 v[210:211], v[192:195], off
	s_nop 0
	v_cvt_pk_bf16_f32 v192, v196, v197
	v_cvt_pk_bf16_f32 v193, v198, v199
	v_cvt_pk_bf16_f32 v194, v202, v203
	v_cvt_pk_bf16_f32 v195, v200, v201
	global_store_dwordx4 v[210:211], v[192:195], off offset:128
	s_nop 1
	v_or_b32_e32 v208, 48, v147
	v_lshlrev_b32_e32 v192, 6, v208
	v_and_or_b32 v192, v192, s12, v144
	v_lshlrev_b32_e32 v204, 2, v192
	global_load_dwordx4 v[192:195], v204, s[72:73] offset:16
	global_load_dwordx4 v[196:199], v204, s[72:73]
	global_load_dwordx4 v[200:203], v204, s[74:75] offset:16
	s_nop 0
	global_load_dwordx4 v[204:207], v204, s[74:75]
	s_waitcnt vmcnt(6)
; __device__ __forceinline__ v4u pk8(f32x4 a, f32x4 b) { v4u w; w.x = pk2(a[0], a[1]); w.y = pk2(a[2], a[3]); w.z = pk2(b[0], b[1]); w.w = pk2(b[2], b[3]); return w; }
;     __device__ __forceinline__ void operator()(const accv (&acc)[2][2][4][2], const pg8::Unit& u, int wr, int wc, int fr, int fq) const {
;     ...
;                 for (int m = 0; m < 4; ++m) { const int row = row0 + ai * 128 + m * 16, pos = row & 4095;
;                     f32x4 o1[2], o2[2];
; #pragma unroll
;                     for (int n = 0; n < 2; ++n) { const f32x4 cv = *(const f32x4*)(rc + (unsigned)(pos * 64 + d0 + 4 * n)), sv = *(const f32x4*)(rs + (unsigned)(pos * 64 + d0 + 4 * n));
;                         const f32x4 x1 = acc[ai][0][m][n], x2 = acc[ai][1][m][n];
;                         o1[n] = (x1 * cv - x2 * sv) * sc; o2[n] = (x2 * cv + x1 * sv) * sc; }
;                     bf16* p = dst + (unsigned)(row * 1024 + head * 128 + d0);
;                     *(v4u*)p = pk8(o1[0], o1[1]); *(v4u*)(p + 64) = pk8(o2[0], o2[1]);
;                     asm volatile("" ::: "memory"); }
	v_pk_mul_f32 v[164:165], v[78:79], v[162:163]
	v_pk_mul_f32 v[162:163], v[102:103], v[162:163]
	v_pk_mul_f32 v[166:167], v[76:77], v[160:161]
	v_pk_fma_f32 v[164:165], v[102:103], v[154:155], v[164:165] neg_lo:[0,0,1] neg_hi:[0,0,1]
	v_pk_mul_f32 v[160:161], v[100:101], v[160:161]
	v_pk_fma_f32 v[154:155], v[78:79], v[154:155], v[162:163]
	v_pk_mul_f32 v[162:163], v[72:73], v[156:157]
	v_pk_mul_f32 v[156:157], v[96:97], v[156:157]
	v_pk_fma_f32 v[166:167], v[100:101], v[152:153], v[166:167] neg_lo:[0,0,1] neg_hi:[0,0,1]
	v_pk_fma_f32 v[152:153], v[76:77], v[152:153], v[160:161]
	v_pk_mul_f32 v[160:161], v[74:75], v[158:159]
	v_pk_fma_f32 v[162:163], v[96:97], v[148:149], v[162:163] neg_lo:[0,0,1] neg_hi:[0,0,1]
	v_pk_mul_f32 v[158:159], v[98:99], v[158:159]
	v_pk_fma_f32 v[148:149], v[72:73], v[148:149], v[156:157]
	v_pk_fma_f32 v[160:161], v[98:99], v[150:151], v[160:161] neg_lo:[0,0,1] neg_hi:[0,0,1]
	v_pk_fma_f32 v[150:151], v[74:75], v[150:151], v[158:159]
	v_pk_mul_f32 v[158:159], v[140:141], v[148:149] op_sel_hi:[0,1]
	v_lshlrev_b32_e32 v148, 10, v168
	v_pk_mul_f32 v[164:165], v[140:141], v[164:165] op_sel_hi:[0,1]
	v_pk_mul_f32 v[166:167], v[140:141], v[166:167] op_sel_hi:[0,1]
	v_pk_mul_f32 v[160:161], v[140:141], v[160:161] op_sel_hi:[0,1]
	v_pk_mul_f32 v[162:163], v[140:141], v[162:163] op_sel_hi:[0,1]
	v_or3_b32 v168, v148, s81, v144
	v_pk_mul_f32 v[154:155], v[140:141], v[154:155] op_sel_hi:[0,1]
	v_pk_mul_f32 v[152:153], v[140:141], v[152:153] op_sel_hi:[0,1]
	v_pk_mul_f32 v[156:157], v[140:141], v[150:151] op_sel_hi:[0,1]
	v_lshl_add_u64 v[170:171], v[168:169], 1, s[86:87]
	v_cvt_pk_bf16_f32 v148, v166, v167
	v_cvt_pk_bf16_f32 v149, v164, v165
	v_cvt_pk_bf16_f32 v150, v162, v163
	v_cvt_pk_bf16_f32 v151, v160, v161
	global_store_dwordx4 v[170:171], v[148:151], off
	s_nop 0
	v_cvt_pk_bf16_f32 v148, v152, v153
	v_cvt_pk_bf16_f32 v149, v154, v155
	v_cvt_pk_bf16_f32 v150, v158, v159
	v_cvt_pk_bf16_f32 v151, v156, v157
	global_store_dwordx4 v[170:171], v[148:151], off offset:128
	s_nop 1
	v_add_u32_e32 v168, 0x80, v147
	v_lshlrev_b32_e32 v148, 6, v168
	v_and_or_b32 v148, v148, s96, v144
	v_lshlrev_b32_e32 v160, 2, v148
	global_load_dwordx4 v[148:151], v160, s[72:73] offset:16
	global_load_dwordx4 v[152:155], v160, s[72:73]
	global_load_dwordx4 v[156:159], v160, s[74:75] offset:16
	s_nop 0
	global_load_dwordx4 v[160:163], v160, s[74:75]
	s_waitcnt vmcnt(6)
	v_pk_mul_f32 v[164:165], v[70:71], v[206:207]
	v_pk_mul_f32 v[206:207], v[86:87], v[206:207]
	v_pk_mul_f32 v[166:167], v[68:69], v[204:205]
	v_pk_fma_f32 v[164:165], v[86:87], v[198:199], v[164:165] neg_lo:[0,0,1] neg_hi:[0,0,1]
	v_pk_mul_f32 v[204:205], v[84:85], v[204:205]
	v_pk_fma_f32 v[198:199], v[70:71], v[198:199], v[206:207]
	v_pk_mul_f32 v[206:207], v[64:65], v[200:201]
	v_pk_mul_f32 v[200:201], v[80:81], v[200:201]
	v_pk_fma_f32 v[166:167], v[84:85], v[196:197], v[166:167] neg_lo:[0,0,1] neg_hi:[0,0,1]
	v_pk_fma_f32 v[196:197], v[68:69], v[196:197], v[204:205]
	v_pk_mul_f32 v[204:205], v[66:67], v[202:203]
	v_pk_fma_f32 v[206:207], v[80:81], v[192:193], v[206:207] neg_lo:[0,0,1] neg_hi:[0,0,1]
	v_pk_mul_f32 v[202:203], v[82:83], v[202:203]
	v_pk_fma_f32 v[192:193], v[64:65], v[192:193], v[200:201]
	v_pk_fma_f32 v[204:205], v[82:83], v[194:195], v[204:205] neg_lo:[0,0,1] neg_hi:[0,0,1]
	v_pk_fma_f32 v[194:195], v[66:67], v[194:195], v[202:203]
	v_pk_mul_f32 v[202:203], v[140:141], v[192:193] op_sel_hi:[0,1]
	v_lshlrev_b32_e32 v192, 10, v208
	v_pk_mul_f32 v[164:165], v[140:141], v[164:165] op_sel_hi:[0,1]
	v_pk_mul_f32 v[166:167], v[140:141], v[166:167] op_sel_hi:[0,1]
	v_pk_mul_f32 v[204:205], v[140:141], v[204:205] op_sel_hi:[0,1]
	v_pk_mul_f32 v[206:207], v[140:141], v[206:207] op_sel_hi:[0,1]
	v_or3_b32 v208, v192, s81, v144
	v_pk_mul_f32 v[198:199], v[140:141], v[198:199] op_sel_hi:[0,1]
	v_pk_mul_f32 v[196:197], v[140:141], v[196:197] op_sel_hi:[0,1]
	v_pk_mul_f32 v[200:201], v[140:141], v[194:195] op_sel_hi:[0,1]
	v_lshl_add_u64 v[210:211], v[208:209], 1, s[86:87]
	v_cvt_pk_bf16_f32 v192, v166, v167
	v_cvt_pk_bf16_f32 v193, v164, v165
	v_cvt_pk_bf16_f32 v194, v206, v207
	v_cvt_pk_bf16_f32 v195, v204, v205
	global_store_dwordx4 v[210:211], v[192:195], off
	s_nop 0
	v_cvt_pk_bf16_f32 v192, v196, v197
	v_cvt_pk_bf16_f32 v193, v198, v199
	v_cvt_pk_bf16_f32 v194, v202, v203
	v_cvt_pk_bf16_f32 v195, v200, v201
	global_store_dwordx4 v[210:211], v[192:195], off offset:128
	s_nop 1
	v_add_u32_e32 v208, 0x90, v147
	v_lshlrev_b32_e32 v192, 6, v208
	v_and_or_b32 v192, v192, s2, v144
	v_lshlrev_b32_e32 v204, 2, v192
	global_load_dwordx4 v[192:195], v204, s[72:73] offset:16
	global_load_dwordx4 v[196:199], v204, s[72:73]
	global_load_dwordx4 v[200:203], v204, s[74:75] offset:16
	s_nop 0
	global_load_dwordx4 v[204:207], v204, s[74:75]
	s_waitcnt vmcnt(6)
; __device__ __forceinline__ v4u pk8(f32x4 a, f32x4 b) { v4u w; w.x = pk2(a[0], a[1]); w.y = pk2(a[2], a[3]); w.z = pk2(b[0], b[1]); w.w = pk2(b[2], b[3]); return w; }
;     __device__ __forceinline__ void operator()(const accv (&acc)[2][2][4][2], const pg8::Unit& u, int wr, int wc, int fr, int fq) const {
;     ...
;                 for (int m = 0; m < 4; ++m) { const int row = row0 + ai * 128 + m * 16, pos = row & 4095;
;                     f32x4 o1[2], o2[2];
; #pragma unroll
;                     for (int n = 0; n < 2; ++n) { const f32x4 cv = *(const f32x4*)(rc + (unsigned)(pos * 64 + d0 + 4 * n)), sv = *(const f32x4*)(rs + (unsigned)(pos * 64 + d0 + 4 * n));
;                         const f32x4 x1 = acc[ai][0][m][n], x2 = acc[ai][1][m][n];
;                         o1[n] = (x1 * cv - x2 * sv) * sc; o2[n] = (x2 * cv + x1 * sv) * sc; }
;                     bf16* p = dst + (unsigned)(row * 1024 + head * 128 + d0);
;                     *(v4u*)p = pk8(o1[0], o1[1]); *(v4u*)(p + 64) = pk8(o2[0], o2[1]);
;                     asm volatile("" ::: "memory"); }
	v_pk_mul_f32 v[164:165], v[46:47], v[162:163]
	v_pk_mul_f32 v[162:163], v[62:63], v[162:163]
	v_pk_mul_f32 v[166:167], v[44:45], v[160:161]
	v_pk_fma_f32 v[164:165], v[62:63], v[154:155], v[164:165] neg_lo:[0,0,1] neg_hi:[0,0,1]
	v_pk_mul_f32 v[160:161], v[60:61], v[160:161]
	v_pk_fma_f32 v[154:155], v[46:47], v[154:155], v[162:163]
	v_pk_mul_f32 v[162:163], v[40:41], v[156:157]
	v_pk_mul_f32 v[156:157], v[56:57], v[156:157]
	v_pk_fma_f32 v[166:167], v[60:61], v[152:153], v[166:167] neg_lo:[0,0,1] neg_hi:[0,0,1]
	v_pk_fma_f32 v[152:153], v[44:45], v[152:153], v[160:161]
	v_pk_mul_f32 v[160:161], v[42:43], v[158:159]
	v_pk_fma_f32 v[162:163], v[56:57], v[148:149], v[162:163] neg_lo:[0,0,1] neg_hi:[0,0,1]
	v_pk_mul_f32 v[158:159], v[58:59], v[158:159]
	v_pk_fma_f32 v[148:149], v[40:41], v[148:149], v[156:157]
	v_pk_fma_f32 v[160:161], v[58:59], v[150:151], v[160:161] neg_lo:[0,0,1] neg_hi:[0,0,1]
	v_pk_fma_f32 v[150:151], v[42:43], v[150:151], v[158:159]
	v_pk_mul_f32 v[158:159], v[140:141], v[148:149] op_sel_hi:[0,1]
	v_lshlrev_b32_e32 v148, 10, v168
	v_pk_mul_f32 v[164:165], v[140:141], v[164:165] op_sel_hi:[0,1]
	v_pk_mul_f32 v[166:167], v[140:141], v[166:167] op_sel_hi:[0,1]
	v_pk_mul_f32 v[160:161], v[140:141], v[160:161] op_sel_hi:[0,1]
	v_pk_mul_f32 v[162:163], v[140:141], v[162:163] op_sel_hi:[0,1]
	v_or3_b32 v168, v148, s81, v144
	v_pk_mul_f32 v[154:155], v[140:141], v[154:155] op_sel_hi:[0,1]
	v_pk_mul_f32 v[152:153], v[140:141], v[152:153] op_sel_hi:[0,1]
	v_pk_mul_f32 v[156:157], v[140:141], v[150:151] op_sel_hi:[0,1]
	v_lshl_add_u64 v[170:171], v[168:169], 1, s[86:87]
	v_cvt_pk_bf16_f32 v148, v166, v167
	v_cvt_pk_bf16_f32 v149, v164, v165
	v_cvt_pk_bf16_f32 v150, v162, v163
	v_cvt_pk_bf16_f32 v151, v160, v161
	global_store_dwordx4 v[170:171], v[148:151], off
	s_nop 0
	v_cvt_pk_bf16_f32 v148, v152, v153
	v_cvt_pk_bf16_f32 v149, v154, v155
	v_cvt_pk_bf16_f32 v150, v158, v159
	v_cvt_pk_bf16_f32 v151, v156, v157
	global_store_dwordx4 v[170:171], v[148:151], off offset:128
	s_nop 1
	v_add_u32_e32 v168, 0xa0, v147
	v_lshlrev_b32_e32 v148, 6, v168
	v_and_or_b32 v148, v148, s3, v144
	v_lshlrev_b32_e32 v160, 2, v148
	global_load_dwordx4 v[148:151], v160, s[72:73] offset:16
	global_load_dwordx4 v[152:155], v160, s[72:73]
	global_load_dwordx4 v[156:159], v160, s[74:75] offset:16
	s_nop 0
	global_load_dwordx4 v[160:163], v160, s[74:75]
	s_waitcnt vmcnt(6)
	v_pk_mul_f32 v[164:165], v[30:31], v[206:207]
	v_pk_mul_f32 v[206:207], v[54:55], v[206:207]
	v_pk_mul_f32 v[166:167], v[28:29], v[204:205]
	v_pk_fma_f32 v[164:165], v[54:55], v[198:199], v[164:165] neg_lo:[0,0,1] neg_hi:[0,0,1]
	v_pk_mul_f32 v[204:205], v[52:53], v[204:205]
	v_pk_fma_f32 v[198:199], v[30:31], v[198:199], v[206:207]
	v_pk_mul_f32 v[206:207], v[24:25], v[200:201]
	v_pk_mul_f32 v[200:201], v[48:49], v[200:201]
	v_pk_fma_f32 v[166:167], v[52:53], v[196:197], v[166:167] neg_lo:[0,0,1] neg_hi:[0,0,1]
	v_pk_fma_f32 v[196:197], v[28:29], v[196:197], v[204:205]
	v_pk_mul_f32 v[204:205], v[26:27], v[202:203]
	v_pk_fma_f32 v[206:207], v[48:49], v[192:193], v[206:207] neg_lo:[0,0,1] neg_hi:[0,0,1]
	v_pk_mul_f32 v[202:203], v[50:51], v[202:203]
	v_pk_fma_f32 v[192:193], v[24:25], v[192:193], v[200:201]
	v_pk_fma_f32 v[204:205], v[50:51], v[194:195], v[204:205] neg_lo:[0,0,1] neg_hi:[0,0,1]
	v_pk_fma_f32 v[194:195], v[26:27], v[194:195], v[202:203]
	v_pk_mul_f32 v[202:203], v[140:141], v[192:193] op_sel_hi:[0,1]
	v_lshlrev_b32_e32 v192, 10, v208
	v_pk_mul_f32 v[164:165], v[140:141], v[164:165] op_sel_hi:[0,1]
	v_pk_mul_f32 v[166:167], v[140:141], v[166:167] op_sel_hi:[0,1]
	v_pk_mul_f32 v[204:205], v[140:141], v[204:205] op_sel_hi:[0,1]
	v_pk_mul_f32 v[206:207], v[140:141], v[206:207] op_sel_hi:[0,1]
	v_or3_b32 v208, v192, s81, v144
	v_pk_mul_f32 v[198:199], v[140:141], v[198:199] op_sel_hi:[0,1]
	v_pk_mul_f32 v[196:197], v[140:141], v[196:197] op_sel_hi:[0,1]
	v_pk_mul_f32 v[200:201], v[140:141], v[194:195] op_sel_hi:[0,1]
	v_lshl_add_u64 v[210:211], v[208:209], 1, s[86:87]
	v_cvt_pk_bf16_f32 v192, v166, v167
	v_cvt_pk_bf16_f32 v193, v164, v165
	v_cvt_pk_bf16_f32 v194, v206, v207
	v_cvt_pk_bf16_f32 v195, v204, v205
	global_store_dwordx4 v[210:211], v[192:195], off
	v_add_u32_e32 v147, 0xb0, v147
	v_cvt_pk_bf16_f32 v192, v196, v197
	v_cvt_pk_bf16_f32 v193, v198, v199
	v_cvt_pk_bf16_f32 v194, v202, v203
	v_cvt_pk_bf16_f32 v195, v200, v201
	global_store_dwordx4 v[210:211], v[192:195], off offset:128
	s_nop 1
	v_mov_b32_e32 v208, v147
	v_lshlrev_b32_e32 v192, 6, v208
	v_and_or_b32 v192, v192, s12, v144
	v_lshlrev_b32_e32 v204, 2, v192
	global_load_dwordx4 v[192:195], v204, s[72:73] offset:16
	global_load_dwordx4 v[196:199], v204, s[72:73]
	global_load_dwordx4 v[200:203], v204, s[74:75] offset:16
	s_nop 0
	global_load_dwordx4 v[204:207], v204, s[74:75]
	s_waitcnt vmcnt(6)
; __device__ __forceinline__ v4u pk8(f32x4 a, f32x4 b) { v4u w; w.x = pk2(a[0], a[1]); w.y = pk2(a[2], a[3]); w.z = pk2(b[0], b[1]); w.w = pk2(b[2], b[3]); return w; }
;     __device__ __forceinline__ void operator()(const accv (&acc)[2][2][4][2], const pg8::Unit& u, int wr, int wc, int fr, int fq) const {
;     ...
;                 for (int m = 0; m < 4; ++m) { const int row = row0 + ai * 128 + m * 16, pos = row & 4095;
;                     f32x4 o1[2], o2[2];
; #pragma unroll
;                     for (int n = 0; n < 2; ++n) { const f32x4 cv = *(const f32x4*)(rc + (unsigned)(pos * 64 + d0 + 4 * n)), sv = *(const f32x4*)(rs + (unsigned)(pos * 64 + d0 + 4 * n));
;                         const f32x4 x1 = acc[ai][0][m][n], x2 = acc[ai][1][m][n];
;                         o1[n] = (x1 * cv - x2 * sv) * sc; o2[n] = (x2 * cv + x1 * sv) * sc; }
;                     bf16* p = dst + (unsigned)(row * 1024 + head * 128 + d0);
;                     *(v4u*)p = pk8(o1[0], o1[1]); *(v4u*)(p + 64) = pk8(o2[0], o2[1]);
;                     asm volatile("" ::: "memory"); }
	v_pk_mul_f32 v[164:165], v[14:15], v[162:163]
	v_pk_mul_f32 v[162:163], v[38:39], v[162:163]
	v_pk_mul_f32 v[166:167], v[12:13], v[160:161]
	v_pk_fma_f32 v[164:165], v[38:39], v[154:155], v[164:165] neg_lo:[0,0,1] neg_hi:[0,0,1]
	v_pk_mul_f32 v[160:161], v[36:37], v[160:161]
	v_pk_fma_f32 v[154:155], v[14:15], v[154:155], v[162:163]
	v_pk_mul_f32 v[162:163], v[8:9], v[156:157]
	v_pk_mul_f32 v[156:157], v[32:33], v[156:157]
	v_pk_fma_f32 v[166:167], v[36:37], v[152:153], v[166:167] neg_lo:[0,0,1] neg_hi:[0,0,1]
	v_pk_fma_f32 v[152:153], v[12:13], v[152:153], v[160:161]
	v_pk_mul_f32 v[160:161], v[10:11], v[158:159]
	v_pk_fma_f32 v[162:163], v[32:33], v[148:149], v[162:163] neg_lo:[0,0,1] neg_hi:[0,0,1]
	v_pk_mul_f32 v[158:159], v[34:35], v[158:159]
	v_pk_fma_f32 v[148:149], v[8:9], v[148:149], v[156:157]
	v_pk_fma_f32 v[160:161], v[34:35], v[150:151], v[160:161] neg_lo:[0,0,1] neg_hi:[0,0,1]
	v_pk_fma_f32 v[150:151], v[10:11], v[150:151], v[158:159]
	v_pk_mul_f32 v[158:159], v[140:141], v[148:149] op_sel_hi:[0,1]
	v_lshlrev_b32_e32 v148, 10, v168
	v_pk_mul_f32 v[164:165], v[140:141], v[164:165] op_sel_hi:[0,1]
	v_pk_mul_f32 v[166:167], v[140:141], v[166:167] op_sel_hi:[0,1]
	v_pk_mul_f32 v[160:161], v[140:141], v[160:161] op_sel_hi:[0,1]
	v_pk_mul_f32 v[162:163], v[140:141], v[162:163] op_sel_hi:[0,1]
	v_or3_b32 v168, v148, s81, v144
	v_pk_mul_f32 v[154:155], v[140:141], v[154:155] op_sel_hi:[0,1]
	v_pk_mul_f32 v[152:153], v[140:141], v[152:153] op_sel_hi:[0,1]
	v_pk_mul_f32 v[156:157], v[140:141], v[150:151] op_sel_hi:[0,1]
	v_lshl_add_u64 v[170:171], v[168:169], 1, s[86:87]
	v_cvt_pk_bf16_f32 v148, v166, v167
	v_cvt_pk_bf16_f32 v149, v164, v165
	v_cvt_pk_bf16_f32 v150, v162, v163
	v_cvt_pk_bf16_f32 v151, v160, v161
	global_store_dwordx4 v[170:171], v[148:151], off
	s_nop 1
	v_cvt_pk_bf16_f32 v148, v152, v153
	v_cvt_pk_bf16_f32 v149, v154, v155
	v_cvt_pk_bf16_f32 v150, v158, v159
	v_cvt_pk_bf16_f32 v151, v156, v157
	global_store_dwordx4 v[170:171], v[148:151], off offset:128
	s_nop 1
	s_waitcnt vmcnt(2)
	v_pk_mul_f32 v[164:165], v[6:7], v[206:207]
	v_pk_mul_f32 v[166:167], v[4:5], v[204:205]
	v_pk_mul_f32 v[206:207], v[22:23], v[206:207]
	v_pk_mul_f32 v[204:205], v[20:21], v[204:205]
	v_pk_fma_f32 v[164:165], v[22:23], v[198:199], v[164:165] neg_lo:[0,0,1] neg_hi:[0,0,1]
	v_pk_fma_f32 v[166:167], v[20:21], v[196:197], v[166:167] neg_lo:[0,0,1] neg_hi:[0,0,1]
	v_pk_fma_f32 v[198:199], v[6:7], v[198:199], v[206:207]
	v_pk_fma_f32 v[196:197], v[4:5], v[196:197], v[204:205]
	v_pk_mul_f32 v[204:205], v[2:3], v[202:203]
	v_pk_mul_f32 v[206:207], v[0:1], v[200:201]
	v_pk_mul_f32 v[202:203], v[18:19], v[202:203]
	v_pk_mul_f32 v[200:201], v[16:17], v[200:201]
	v_pk_fma_f32 v[204:205], v[18:19], v[194:195], v[204:205] neg_lo:[0,0,1] neg_hi:[0,0,1]
	v_pk_fma_f32 v[206:207], v[16:17], v[192:193], v[206:207] neg_lo:[0,0,1] neg_hi:[0,0,1]
	v_pk_fma_f32 v[194:195], v[2:3], v[194:195], v[202:203]
	v_pk_fma_f32 v[192:193], v[0:1], v[192:193], v[200:201]
	v_pk_mul_f32 v[164:165], v[140:141], v[164:165] op_sel_hi:[0,1]
	v_pk_mul_f32 v[166:167], v[140:141], v[166:167] op_sel_hi:[0,1]
	v_pk_mul_f32 v[198:199], v[140:141], v[198:199] op_sel_hi:[0,1]
	v_pk_mul_f32 v[196:197], v[140:141], v[196:197] op_sel_hi:[0,1]
	v_pk_mul_f32 v[204:205], v[140:141], v[204:205] op_sel_hi:[0,1]
	v_pk_mul_f32 v[206:207], v[140:141], v[206:207] op_sel_hi:[0,1]
	v_pk_mul_f32 v[200:201], v[140:141], v[194:195] op_sel_hi:[0,1]
	v_pk_mul_f32 v[202:203], v[140:141], v[192:193] op_sel_hi:[0,1]
	v_lshlrev_b32_e32 v140, 10, v147
	v_or3_b32 v208, v140, s81, v144
	v_lshl_add_u64 v[210:211], v[208:209], 1, s[86:87]
	v_cvt_pk_bf16_f32 v192, v166, v167
	v_cvt_pk_bf16_f32 v193, v164, v165
	v_cvt_pk_bf16_f32 v194, v206, v207
	v_cvt_pk_bf16_f32 v195, v204, v205
	global_store_dwordx4 v[210:211], v[192:195], off
	s_nop 1
	v_cvt_pk_bf16_f32 v192, v196, v197
	v_cvt_pk_bf16_f32 v193, v198, v199
	v_cvt_pk_bf16_f32 v194, v202, v203
	v_cvt_pk_bf16_f32 v195, v200, v201
	global_store_dwordx4 v[210:211], v[192:195], off offset:128
	s_mov_b32 s93, 0x800000
	s_cbranch_execnz .LBB0_546
